# gate GEMM (gz): the 32 KB gate weight block is staged once per workgroup in LDS instead of being re-read from global by every wave
# speedup vs baseline: 1.0097x; 1.0097x over previous
; __device__ __forceinline__ int opaque_tid() { int t = threadIdx.x; asm volatile("" : "+v"(t)); return t; }
; __device__ __forceinline__ void gz_gemm(const bf16_t* Wz  , const bf16_t* hn  , float* gz, int G) {
;     const int tid = opaque_tid(), lane = tid & 63, wid = __builtin_amdgcn_readfirstlane(tid >> 6);
;     for (int task = blockIdx.x * NWAVES + wid; task < MT / 16; task += G * NWAVES) {
;         const bf16_t* ap = Wz + (size_t)(lane & 15) * DM + (lane >> 4) * 8;
;         const bf16_t* bp = hn + (size_t)(task * 16 + (lane & 15)) * DM + (lane >> 4) * 8;
;         f32x4 acc0 = {0.f, 0.f, 0.f, 0.f}, acc1 = {0.f, 0.f, 0.f, 0.f};
; #pragma unroll 8
;         for (int k = 0; k < DM; k += 64) {
;             const bf16x8 a0 = *(const bf16x8*)(ap + k), b0 = *(const bf16x8*)(bp + k), a1 = *(const bf16x8*)(ap + k + 32), b1 = *(const bf16x8*)(bp + k + 32);
;             acc0 = __builtin_amdgcn_mfma_f32_16x16x32_bf16(a0, b0, acc0, 0, 0, 0); acc1 = __builtin_amdgcn_mfma_f32_16x16x32_bf16(a1, b1, acc1, 0, 0, 0); }
;         const f32x4 r = acc0 + acc1;
;         *(f32x4*)(gz + (size_t)(task * 16 + (lane & 15)) * 16 + (lane >> 4) * 4) = r;
;     }
; }
.LBB0_181:
	s_mov_b64 s[8:9], s[90:91]
	v_mov_b32_e32 v0, v194
	s_nop 0
	v_readfirstlane_b32 s4, v0
	s_ashr_i32 s5, s4, 6
	v_readlane_b32 s4, v253, 4
	s_add_i32 s4, s5, s4
	s_cmpk_gt_i32 s4, 0x800
	s_cbranch_scc1 .LBB0_186
	s_load_dwordx2 s[8:9], s[8:9], 0x88
	v_and_b32_e32 v17, 15, v0
	v_and_b32_e32 v0, 48, v0
	s_lshl_b32 s5, s5, 4
	v_readlane_b32 s6, v254, 14
	s_add_i32 s5, s6, s5
	s_waitcnt lgkmcnt(0)
	v_lshl_add_u64 v[2:3], s[8:9], 0, v[0:1]
	s_mov_b64 s[10:11], 0x16640000
	v_lshl_add_u64 v[10:11], v[2:3], 0, s[10:11]
	s_add_u32 s10, s8, s3
	v_lshlrev_b32_e32 v2, 11, v17
	v_mov_b32_e32 v3, v1
	s_addc_u32 s11, s9, s2
	v_lshl_add_u64 v[2:3], s[10:11], 0, v[2:3]
	s_mov_b64 s[2:3], 0x1700200
	v_add_u32_e32 v12, s5, v17
	v_lshl_add_u64 v[14:15], v[2:3], 0, s[2:3]
	s_add_u32 s12, s10, 0x1700000
	s_addc_u32 s13, s11, 0
	v_readfirstlane_b32 s14, v194
	s_lshr_b32 s14, s14, 6
	s_mul_i32 s15, s14, 0x1020
	s_lshl_b32 s14, s14, 12
	s_add_u32 s12, s12, s14
	s_addc_u32 s13, s13, 0
	v_lshlrev_b32_e32 v42, 4, v200
	s_mov_b32 m0, s15
	s_nop 0
	global_load_lds_dwordx4 v42, s[12:13]
	global_load_lds_dwordx4 v42, s[12:13] offset:1024
	s_add_i32 m0, s15, 16
	s_nop 0
	global_load_lds_dwordx4 v42, s[12:13] offset:2048
	global_load_lds_dwordx4 v42, s[12:13] offset:3072
	v_mul_u32_u24_e32 v43, 0x810, v17
	v_add_u32_e32 v43, v43, v0
	s_waitcnt vmcnt(0)
	s_barrier
; __device__ __forceinline__ void gz_gemm(const bf16_t* Wz  , const bf16_t* hn  , float* gz, int G) {
;     ...
;     for (int task = blockIdx.x * NWAVES + wid; task < MT / 16; task += G * NWAVES) {
;         const bf16_t* ap = Wz + (size_t)(lane & 15) * DM + (lane >> 4) * 8;
;         const bf16_t* bp = hn + (size_t)(task * 16 + (lane & 15)) * DM + (lane >> 4) * 8;
;         f32x4 acc0 = {0.f, 0.f, 0.f, 0.f}, acc1 = {0.f, 0.f, 0.f, 0.f};
; #pragma unroll 8
;         for (int k = 0; k < DM; k += 64) {
;             const bf16x8 a0 = *(const bf16x8*)(ap + k), b0 = *(const bf16x8*)(bp + k), a1 = *(const bf16x8*)(ap + k + 32), b1 = *(const bf16x8*)(bp + k + 32);
;             acc0 = __builtin_amdgcn_mfma_f32_16x16x32_bf16(a0, b0, acc0, 0, 0, 0); acc1 = __builtin_amdgcn_mfma_f32_16x16x32_bf16(a1, b1, acc1, 0, 0, 0); }
;         const f32x4 r = acc0 + acc1;
;         *(f32x4*)(gz + (size_t)(task * 16 + (lane & 15)) * 16 + (lane >> 4) * 4) = r;
;     }
.LBB0_183:
	v_ashrrev_i32_e32 v13, 31, v12
	v_lshlrev_b64 v[2:3], 11, v[12:13]
	v_lshl_add_u64 v[18:19], s[8:9], 0, v[2:3]
	v_mov_b32_e32 v2, 0
	s_movk_i32 s2, 0xffc0
	v_mov_b64_e32 v[20:21], v[14:15]
	v_mov_b32_e32 v3, v2
	v_mov_b32_e32 v4, v2
	v_mov_b32_e32 v5, v2
	v_mov_b32_e32 v6, v2
	v_mov_b32_e32 v7, v2
	v_mov_b32_e32 v8, v2
	v_mov_b32_e32 v9, v2
	v_lshl_add_u64 v[26:27], v[18:19], 0, v[0:1]
	s_mov_b32 s3, 0x6400000
	v_add_co_u32_e32 v40, vcc, s3, v26
	s_nop 1
	v_addc_co_u32_e32 v41, vcc, 0, v27, vcc
	global_load_dwordx4 v[60:63], v[40:41], off
	global_load_dwordx4 v[64:67], v[40:41], off offset:64
	global_load_dwordx4 v[68:71], v[40:41], off offset:128
	global_load_dwordx4 v[72:75], v[40:41], off offset:192
	global_load_dwordx4 v[76:79], v[40:41], off offset:256
	global_load_dwordx4 v[80:83], v[40:41], off offset:320
	global_load_dwordx4 v[84:87], v[40:41], off offset:384
	global_load_dwordx4 v[88:91], v[40:41], off offset:448
	global_load_dwordx4 v[92:95], v[40:41], off offset:512
	global_load_dwordx4 v[96:99], v[40:41], off offset:576
	global_load_dwordx4 v[100:103], v[40:41], off offset:640
	global_load_dwordx4 v[104:107], v[40:41], off offset:704
	ds_read_b128 v[44:47], v43
	ds_read_b128 v[48:51], v43 offset:64
	ds_read_b128 v[52:55], v43 offset:128
	ds_read_b128 v[56:59], v43 offset:192
	s_waitcnt vmcnt(10) lgkmcnt(2)
	v_mfma_f32_16x16x32_bf16 v[2:5], v[44:47], v[60:63], v[2:5]
	v_mfma_f32_16x16x32_bf16 v[6:9], v[48:51], v[64:67], v[6:9]
	global_load_dwordx4 v[60:63], v[40:41], off offset:768
	global_load_dwordx4 v[64:67], v[40:41], off offset:832
	ds_read_b128 v[44:47], v43 offset:256
	ds_read_b128 v[48:51], v43 offset:320
	s_waitcnt vmcnt(10) lgkmcnt(2)
	v_mfma_f32_16x16x32_bf16 v[2:5], v[52:55], v[68:71], v[2:5]
	v_mfma_f32_16x16x32_bf16 v[6:9], v[56:59], v[72:75], v[6:9]
	global_load_dwordx4 v[68:71], v[40:41], off offset:896
	global_load_dwordx4 v[72:75], v[40:41], off offset:960
	ds_read_b128 v[52:55], v43 offset:384
	ds_read_b128 v[56:59], v43 offset:448
	s_waitcnt vmcnt(10) lgkmcnt(2)
	v_mfma_f32_16x16x32_bf16 v[2:5], v[44:47], v[76:79], v[2:5]
	v_mfma_f32_16x16x32_bf16 v[6:9], v[48:51], v[80:83], v[6:9]
	global_load_dwordx4 v[76:79], v[40:41], off offset:1024
	global_load_dwordx4 v[80:83], v[40:41], off offset:1088
	ds_read_b128 v[44:47], v43 offset:512
	ds_read_b128 v[48:51], v43 offset:576
	s_waitcnt vmcnt(10) lgkmcnt(2)
	v_mfma_f32_16x16x32_bf16 v[2:5], v[52:55], v[84:87], v[2:5]
	v_mfma_f32_16x16x32_bf16 v[6:9], v[56:59], v[88:91], v[6:9]
	global_load_dwordx4 v[84:87], v[40:41], off offset:1152
	global_load_dwordx4 v[88:91], v[40:41], off offset:1216
	ds_read_b128 v[52:55], v43 offset:640
	ds_read_b128 v[56:59], v43 offset:704
	s_waitcnt vmcnt(10) lgkmcnt(2)
	v_mfma_f32_16x16x32_bf16 v[2:5], v[44:47], v[92:95], v[2:5]
	v_mfma_f32_16x16x32_bf16 v[6:9], v[48:51], v[96:99], v[6:9]
	global_load_dwordx4 v[92:95], v[40:41], off offset:1280
	global_load_dwordx4 v[96:99], v[40:41], off offset:1344
	ds_read_b128 v[44:47], v43 offset:768
	ds_read_b128 v[48:51], v43 offset:832
	s_waitcnt vmcnt(10) lgkmcnt(2)
	v_mfma_f32_16x16x32_bf16 v[2:5], v[52:55], v[100:103], v[2:5]
	v_mfma_f32_16x16x32_bf16 v[6:9], v[56:59], v[104:107], v[6:9]
	global_load_dwordx4 v[100:103], v[40:41], off offset:1408
	global_load_dwordx4 v[104:107], v[40:41], off offset:1472
	ds_read_b128 v[52:55], v43 offset:896
	ds_read_b128 v[56:59], v43 offset:960
	s_waitcnt vmcnt(10) lgkmcnt(2)
	v_mfma_f32_16x16x32_bf16 v[2:5], v[44:47], v[60:63], v[2:5]
	v_mfma_f32_16x16x32_bf16 v[6:9], v[48:51], v[64:67], v[6:9]
	global_load_dwordx4 v[60:63], v[40:41], off offset:1536
	global_load_dwordx4 v[64:67], v[40:41], off offset:1600
	ds_read_b128 v[44:47], v43 offset:1024
	ds_read_b128 v[48:51], v43 offset:1088
	s_waitcnt vmcnt(10) lgkmcnt(2)
	v_mfma_f32_16x16x32_bf16 v[2:5], v[52:55], v[68:71], v[2:5]
	v_mfma_f32_16x16x32_bf16 v[6:9], v[56:59], v[72:75], v[6:9]
	global_load_dwordx4 v[68:71], v[40:41], off offset:1664
	global_load_dwordx4 v[72:75], v[40:41], off offset:1728
	ds_read_b128 v[52:55], v43 offset:1152
	ds_read_b128 v[56:59], v43 offset:1216
	s_waitcnt vmcnt(10) lgkmcnt(2)
	v_mfma_f32_16x16x32_bf16 v[2:5], v[44:47], v[76:79], v[2:5]
	v_mfma_f32_16x16x32_bf16 v[6:9], v[48:51], v[80:83], v[6:9]
	global_load_dwordx4 v[76:79], v[40:41], off offset:1792
	global_load_dwordx4 v[80:83], v[40:41], off offset:1856
	ds_read_b128 v[44:47], v43 offset:1280
	ds_read_b128 v[48:51], v43 offset:1344
	s_waitcnt vmcnt(10) lgkmcnt(2)
	v_mfma_f32_16x16x32_bf16 v[2:5], v[52:55], v[84:87], v[2:5]
	v_mfma_f32_16x16x32_bf16 v[6:9], v[56:59], v[88:91], v[6:9]
	global_load_dwordx4 v[84:87], v[40:41], off offset:1920
	global_load_dwordx4 v[88:91], v[40:41], off offset:1984
	ds_read_b128 v[52:55], v43 offset:1408
	ds_read_b128 v[56:59], v43 offset:1472
	s_waitcnt vmcnt(10) lgkmcnt(2)
	v_mfma_f32_16x16x32_bf16 v[2:5], v[44:47], v[92:95], v[2:5]
	v_mfma_f32_16x16x32_bf16 v[6:9], v[48:51], v[96:99], v[6:9]
	ds_read_b128 v[44:47], v43 offset:1536
	ds_read_b128 v[48:51], v43 offset:1600
	s_waitcnt vmcnt(8) lgkmcnt(2)
	v_mfma_f32_16x16x32_bf16 v[2:5], v[52:55], v[100:103], v[2:5]
	v_mfma_f32_16x16x32_bf16 v[6:9], v[56:59], v[104:107], v[6:9]
	ds_read_b128 v[52:55], v43 offset:1664
	ds_read_b128 v[56:59], v43 offset:1728
	s_waitcnt vmcnt(6) lgkmcnt(2)
	v_mfma_f32_16x16x32_bf16 v[2:5], v[44:47], v[60:63], v[2:5]
	v_mfma_f32_16x16x32_bf16 v[6:9], v[48:51], v[64:67], v[6:9]
	ds_read_b128 v[44:47], v43 offset:1792
	ds_read_b128 v[48:51], v43 offset:1856
	s_waitcnt vmcnt(4) lgkmcnt(2)
	v_mfma_f32_16x16x32_bf16 v[2:5], v[52:55], v[68:71], v[2:5]
	v_mfma_f32_16x16x32_bf16 v[6:9], v[56:59], v[72:75], v[6:9]
	ds_read_b128 v[52:55], v43 offset:1920
	ds_read_b128 v[56:59], v43 offset:1984
	s_waitcnt vmcnt(2) lgkmcnt(2)
	v_mfma_f32_16x16x32_bf16 v[2:5], v[44:47], v[76:79], v[2:5]
	v_mfma_f32_16x16x32_bf16 v[6:9], v[48:51], v[80:83], v[6:9]
	s_waitcnt vmcnt(0) lgkmcnt(0)
	v_mfma_f32_16x16x32_bf16 v[2:5], v[52:55], v[84:87], v[2:5]
	v_mfma_f32_16x16x32_bf16 v[6:9], v[56:59], v[88:91], v[6:9]
	v_lshl_or_b32 v18, s4, 4, v17
	v_ashrrev_i32_e32 v19, 31, v18
	s_nop 4
	v_pk_add_f32 v[2:3], v[2:3], v[6:7]
	v_lshlrev_b64 v[6:7], 6, v[18:19]
	s_add_i32 s4, s4, s88
	v_readlane_b32 s2, v254, 15
	v_pk_add_f32 v[4:5], v[4:5], v[8:9]
	v_lshl_add_u64 v[6:7], v[10:11], 0, v[6:7]
	s_cmpk_gt_i32 s4, 0x800
	v_add_u32_e32 v12, s2, v12
	global_store_dwordx4 v[6:7], v[2:5], off
	s_cbranch_scc0 .LBB0_183
